# P4 epilogue: final f32 output stores with the nontemporal hint (never re-read)
# baseline (speedup 1.0000x reference)
.LBB0_707:
	global_load_dword v39, v[180:181], off sc1
	global_load_dword v40, v[180:181], off offset:64 sc1
	global_load_dword v41, v[180:181], off offset:128 sc1
	v_lshl_add_u64 v[34:35], v[178:179], 2, s[30:31]
	global_load_dword v178, v[180:181], off offset:192 sc1
	global_load_dword v179, v[180:181], off offset:512 sc1
	global_load_dword v38, v[180:181], off offset:576 sc1
	global_load_dword v37, v[180:181], off offset:640 sc1
	global_load_dword v36, v[180:181], off offset:704 sc1
	v_lshl_add_u64 v[50:51], v[34:35], 0, s[16:17]
	s_waitcnt vmcnt(7)
	v_fmamk_f32 v39, v39, 0x3a000000, v189
	s_waitcnt vmcnt(6)
	v_fmamk_f32 v40, v40, 0x3a000000, v189
	s_waitcnt vmcnt(5)
	v_fmamk_f32 v180, v41, 0x3a000000, v189
	v_mul_f32_e32 v41, 0x4f800000, v39
	v_cmp_gt_f32_e32 vcc, s53, v39
	v_mul_f32_e32 v42, 0x4f800000, v40
	v_cmp_gt_f32_e64 s[4:5], s53, v40
	v_cndmask_b32_e32 v39, v39, v41, vcc
	v_sqrt_f32_e32 v41, v39
	v_cndmask_b32_e64 v40, v40, v42, s[4:5]
	v_sqrt_f32_e32 v42, v40
	v_mul_f32_e32 v181, 0x4f800000, v180
	v_add_u32_e32 v43, -1, v41
	v_fma_f32 v47, -v43, v41, v39
	v_add_u32_e32 v45, -1, v42
	v_add_u32_e32 v44, 1, v41
	v_fma_f32 v183, -v45, v42, v40
	v_cmp_ge_f32_e64 s[6:7], 0, v47
	v_add_u32_e32 v46, 1, v42
	v_fma_f32 v182, -v44, v41, v39
	v_cndmask_b32_e64 v41, v41, v43, s[6:7]
	v_cmp_ge_f32_e64 s[6:7], 0, v183
	v_fma_f32 v191, -v46, v42, v40
	s_waitcnt vmcnt(2)
	v_fmamk_f32 v38, v38, 0x3a000000, v189
	v_cndmask_b32_e64 v42, v42, v45, s[6:7]
	v_cmp_lt_f32_e64 s[6:7], 0, v182
	s_waitcnt vmcnt(1)
	v_fmamk_f32 v37, v37, 0x3a000000, v189
	v_cndmask_b32_e64 v41, v41, v44, s[6:7]
	v_cmp_lt_f32_e64 s[6:7], 0, v191
	v_mul_f32_e32 v43, 0x37800000, v41
	v_cndmask_b32_e32 v41, v41, v43, vcc
	v_cndmask_b32_e64 v42, v42, v46, s[6:7]
	v_mul_f32_e32 v44, 0x37800000, v42
	v_cmp_class_f32_e32 vcc, v39, v190
	v_cndmask_b32_e64 v42, v42, v44, s[4:5]
	s_nop 0
	v_cndmask_b32_e32 v39, v41, v39, vcc
	v_cmp_class_f32_e32 vcc, v40, v190
	s_nop 1
	v_cndmask_b32_e32 v41, v42, v40, vcc
	v_div_scale_f32 v40, s[4:5], v39, v39, 1.0
	v_div_scale_f32 v43, s[4:5], v41, v41, 1.0
	v_rcp_f32_e32 v44, v40
	v_rcp_f32_e32 v45, v43
	v_div_scale_f32 v42, vcc, 1.0, v39, 1.0
	v_fma_f32 v47, -v40, v44, 1.0
	v_fma_f32 v182, -v43, v45, 1.0
	v_fmac_f32_e32 v44, v47, v44
	v_div_scale_f32 v46, s[4:5], 1.0, v41, 1.0
	v_fmac_f32_e32 v45, v182, v45
	v_mul_f32_e32 v47, v42, v44
	v_mul_f32_e32 v182, v46, v45
	v_fma_f32 v183, -v40, v47, v42
	v_fma_f32 v191, -v43, v182, v46
	v_fmac_f32_e32 v47, v183, v44
	v_fmac_f32_e32 v182, v191, v45
	v_fma_f32 v40, -v40, v47, v42
	v_fma_f32 v42, -v43, v182, v46
	v_div_fmas_f32 v40, v40, v44, v47
	s_mov_b64 vcc, s[4:5]
	v_div_fixup_f32 v40, v40, v39, 1.0
	v_div_fmas_f32 v39, v42, v45, v182
	v_pk_mul_f32 v[44:45], v[176:177], v[40:41] op_sel_hi:[1,0]
	v_pk_mul_f32 v[42:43], v[168:169], v[40:41] op_sel_hi:[1,0]
	v_pk_mul_f32 v[168:169], v[174:175], v[40:41] op_sel_hi:[1,0]
	v_div_fixup_f32 v174, v39, v41, 1.0
	v_pk_mul_f32 v[46:47], v[166:167], v[40:41] op_sel_hi:[1,0]
	v_pk_mul_f32 v[166:167], v[172:173], v[40:41] op_sel_hi:[1,0]
	v_pk_mul_f32 v[164:165], v[164:165], v[40:41] op_sel_hi:[1,0]
	v_pk_mul_f32 v[170:171], v[170:171], v[40:41] op_sel_hi:[1,0]
	v_pk_mul_f32 v[172:173], v[162:163], v[40:41] op_sel_hi:[1,0]
	v_pk_mul_f32 v[42:43], v[14:15], v[42:43]
	v_pk_mul_f32 v[40:41], v[12:13], v[44:45]
	v_pk_mul_f32 v[44:45], v[8:9], v[168:169]
	v_pk_mul_f32 v[140:141], v[140:141], v[174:175] op_sel_hi:[1,0]
	v_pk_mul_f32 v[142:143], v[142:143], v[174:175] op_sel_hi:[1,0]
	v_pk_mul_f32 v[136:137], v[136:137], v[174:175] op_sel_hi:[1,0]
	v_cmp_gt_f32_e32 vcc, s53, v180
	v_pk_mul_f32 v[46:47], v[10:11], v[46:47]
	v_pk_mul_f32 v[164:165], v[6:7], v[164:165]
	v_pk_mul_f32 v[162:163], v[4:5], v[166:167]
	v_pk_mul_f32 v[168:169], v[2:3], v[172:173]
	v_pk_mul_f32 v[166:167], v[0:1], v[170:171]
	v_pk_mul_f32 v[138:139], v[138:139], v[174:175] op_sel_hi:[1,0]
	v_pk_mul_f32 v[132:133], v[132:133], v[174:175] op_sel_hi:[1,0]
	v_pk_mul_f32 v[134:135], v[134:135], v[174:175] op_sel_hi:[1,0]
	global_store_dwordx4 v[34:35], v[40:43], off nt
	global_store_dwordx4 v[34:35], v[44:47], off offset:16 nt
	global_store_dwordx4 v[34:35], v[162:165], off offset:512 nt
	global_store_dwordx4 v[34:35], v[166:169], off offset:528 nt
	v_pk_mul_f32 v[42:43], v[14:15], v[142:143]
	v_pk_mul_f32 v[40:41], v[12:13], v[140:141]
	v_pk_mul_f32 v[44:45], v[8:9], v[136:137]
	v_cndmask_b32_e32 v39, v180, v181, vcc
	v_pk_mul_f32 v[46:47], v[10:11], v[138:139]
	v_pk_mul_f32 v[134:135], v[6:7], v[134:135]
	v_pk_mul_f32 v[132:133], v[4:5], v[132:133]
	flat_store_dwordx4 v[50:51], v[40:43] nt
	flat_store_dwordx4 v[50:51], v[44:47] offset:16 nt
	flat_store_dwordx4 v[50:51], v[132:135] offset:512 nt
	v_pk_mul_f32 v[34:35], v[130:131], v[174:175] op_sel_hi:[1,0]
	v_sqrt_f32_e32 v44, v39
	v_pk_mul_f32 v[42:43], v[2:3], v[34:35]
	v_pk_mul_f32 v[128:129], v[128:129], v[174:175] op_sel_hi:[1,0]
	v_add_u32_e32 v34, -1, v44
	v_fma_f32 v35, -v34, v44, v39
	v_cmp_ge_f32_e64 s[4:5], 0, v35
	v_add_u32_e32 v35, 1, v44
	v_pk_mul_f32 v[40:41], v[0:1], v[128:129]
	v_cndmask_b32_e64 v34, v44, v34, s[4:5]
	v_fma_f32 v44, -v35, v44, v39
	v_cmp_lt_f32_e64 s[4:5], 0, v44
	flat_store_dwordx4 v[50:51], v[40:43] offset:528 nt
	s_nop 0
	v_cndmask_b32_e64 v34, v34, v35, s[4:5]
	v_mul_f32_e32 v35, 0x37800000, v34
	v_cndmask_b32_e32 v34, v34, v35, vcc
	v_cmp_class_f32_e32 vcc, v39, v190
	s_nop 1
	v_cndmask_b32_e32 v39, v34, v39, vcc
	v_div_scale_f32 v44, s[4:5], v39, v39, 1.0
	v_rcp_f32_e32 v45, v44
	v_lshl_add_u64 v[34:35], v[50:51], 0, s[16:17]
	v_fma_f32 v40, -v44, v45, 1.0
	v_fmac_f32_e32 v45, v40, v45
	v_div_scale_f32 v40, vcc, 1.0, v39, 1.0
	v_mul_f32_e32 v41, v40, v45
	v_fma_f32 v42, -v44, v41, v40
	v_fmac_f32_e32 v41, v42, v45
	v_fma_f32 v40, -v44, v41, v40
	v_div_fmas_f32 v40, v40, v45, v41
	v_div_fixup_f32 v44, v40, v39, 1.0
	v_pk_mul_f32 v[40:41], v[124:125], v[44:45] op_sel_hi:[1,0]
	v_pk_mul_f32 v[42:43], v[126:127], v[44:45] op_sel_hi:[1,0]
	v_pk_mul_f32 v[40:41], v[12:13], v[40:41]
	v_pk_mul_f32 v[42:43], v[14:15], v[42:43]
	flat_store_dwordx4 v[34:35], v[40:43] nt
	v_fmamk_f32 v39, v178, 0x3a000000, v189
	v_cmp_gt_f32_e32 vcc, s53, v39
	v_pk_mul_f32 v[40:41], v[120:121], v[44:45] op_sel_hi:[1,0]
	v_pk_mul_f32 v[42:43], v[122:123], v[44:45] op_sel_hi:[1,0]
	v_pk_mul_f32 v[40:41], v[8:9], v[40:41]
	v_pk_mul_f32 v[42:43], v[10:11], v[42:43]
	flat_store_dwordx4 v[34:35], v[40:43] offset:16 nt
	s_nop 1
	v_pk_mul_f32 v[40:41], v[116:117], v[44:45] op_sel_hi:[1,0]
	v_pk_mul_f32 v[42:43], v[118:119], v[44:45] op_sel_hi:[1,0]
	v_pk_mul_f32 v[40:41], v[4:5], v[40:41]
	v_pk_mul_f32 v[42:43], v[6:7], v[42:43]
	flat_store_dwordx4 v[34:35], v[40:43] offset:512 nt
	s_nop 1
	v_mul_f32_e32 v42, 0x4f800000, v39
	v_cndmask_b32_e32 v39, v39, v42, vcc
	v_pk_mul_f32 v[40:41], v[112:113], v[44:45] op_sel_hi:[1,0]
	v_sqrt_f32_e32 v45, v39
	v_pk_mul_f32 v[40:41], v[0:1], v[40:41]
	v_pk_mul_f32 v[42:43], v[114:115], v[44:45] op_sel_hi:[1,0]
	v_add_u32_e32 v44, -1, v45
	v_fma_f32 v46, -v44, v45, v39
	v_cmp_ge_f32_e64 s[4:5], 0, v46
	v_add_u32_e32 v46, 1, v45
	v_pk_mul_f32 v[42:43], v[2:3], v[42:43]
	v_cndmask_b32_e64 v44, v45, v44, s[4:5]
	v_fma_f32 v45, -v46, v45, v39
	v_cmp_lt_f32_e64 s[4:5], 0, v45
	flat_store_dwordx4 v[34:35], v[40:43] offset:528 nt
	v_lshl_add_u64 v[34:35], v[34:35], 0, s[16:17]
	v_cndmask_b32_e64 v44, v44, v46, s[4:5]
	v_mul_f32_e32 v45, 0x37800000, v44
	v_cndmask_b32_e32 v44, v44, v45, vcc
	v_cmp_class_f32_e32 vcc, v39, v190
	s_nop 1
	v_cndmask_b32_e32 v39, v44, v39, vcc
	v_div_scale_f32 v44, s[4:5], v39, v39, 1.0
	v_rcp_f32_e32 v45, v44
	s_nop 0
	v_fma_f32 v40, -v44, v45, 1.0
	v_fmac_f32_e32 v45, v40, v45
	v_div_scale_f32 v40, vcc, 1.0, v39, 1.0
	v_mul_f32_e32 v41, v40, v45
	v_fma_f32 v42, -v44, v41, v40
	v_fmac_f32_e32 v41, v42, v45
	v_fma_f32 v40, -v44, v41, v40
	v_div_fmas_f32 v40, v40, v45, v41
	v_div_fixup_f32 v44, v40, v39, 1.0
	v_pk_mul_f32 v[40:41], v[108:109], v[44:45] op_sel_hi:[1,0]
	v_pk_mul_f32 v[42:43], v[110:111], v[44:45] op_sel_hi:[1,0]
	v_pk_mul_f32 v[40:41], v[12:13], v[40:41]
	v_pk_mul_f32 v[42:43], v[14:15], v[42:43]
	flat_store_dwordx4 v[34:35], v[40:43] nt
	v_fmamk_f32 v39, v179, 0x3a000000, v189
	v_cmp_gt_f32_e32 vcc, s53, v39
	v_pk_mul_f32 v[40:41], v[104:105], v[44:45] op_sel_hi:[1,0]
	v_pk_mul_f32 v[42:43], v[106:107], v[44:45] op_sel_hi:[1,0]
	v_pk_mul_f32 v[40:41], v[8:9], v[40:41]
	v_pk_mul_f32 v[42:43], v[10:11], v[42:43]
	flat_store_dwordx4 v[34:35], v[40:43] offset:16 nt
	s_nop 1
	v_pk_mul_f32 v[40:41], v[100:101], v[44:45] op_sel_hi:[1,0]
	v_pk_mul_f32 v[42:43], v[102:103], v[44:45] op_sel_hi:[1,0]
	v_pk_mul_f32 v[40:41], v[4:5], v[40:41]
	v_pk_mul_f32 v[42:43], v[6:7], v[42:43]
	flat_store_dwordx4 v[34:35], v[40:43] offset:512 nt
	s_nop 1
	v_mul_f32_e32 v42, 0x4f800000, v39
	v_cndmask_b32_e32 v39, v39, v42, vcc
	v_pk_mul_f32 v[40:41], v[96:97], v[44:45] op_sel_hi:[1,0]
	v_sqrt_f32_e32 v45, v39
	v_pk_mul_f32 v[40:41], v[0:1], v[40:41]
	v_pk_mul_f32 v[42:43], v[98:99], v[44:45] op_sel_hi:[1,0]
	v_add_u32_e32 v44, -1, v45
	v_fma_f32 v46, -v44, v45, v39
	v_cmp_ge_f32_e64 s[4:5], 0, v46
	v_add_u32_e32 v46, 1, v45
	v_pk_mul_f32 v[42:43], v[2:3], v[42:43]
	v_cndmask_b32_e64 v44, v45, v44, s[4:5]
	v_fma_f32 v45, -v46, v45, v39
	v_cmp_lt_f32_e64 s[4:5], 0, v45
	flat_store_dwordx4 v[34:35], v[40:43] offset:528 nt
	v_lshl_add_u64 v[34:35], v[34:35], 0, s[20:21]
	v_cndmask_b32_e64 v44, v44, v46, s[4:5]
	v_mul_f32_e32 v45, 0x37800000, v44
	v_cndmask_b32_e32 v44, v44, v45, vcc
	v_cmp_class_f32_e32 vcc, v39, v190
	s_nop 1
	v_cndmask_b32_e32 v39, v44, v39, vcc
	v_div_scale_f32 v44, s[4:5], v39, v39, 1.0
	v_rcp_f32_e32 v45, v44
	s_nop 0
	v_fma_f32 v40, -v44, v45, 1.0
	v_fmac_f32_e32 v45, v40, v45
	v_div_scale_f32 v40, vcc, 1.0, v39, 1.0
	v_mul_f32_e32 v41, v40, v45
	v_fma_f32 v42, -v44, v41, v40
	v_fmac_f32_e32 v41, v42, v45
	v_fma_f32 v40, -v44, v41, v40
	v_div_fmas_f32 v40, v40, v45, v41
	v_div_fixup_f32 v44, v40, v39, 1.0
	v_pk_mul_f32 v[40:41], v[92:93], v[44:45] op_sel_hi:[1,0]
	v_pk_mul_f32 v[42:43], v[94:95], v[44:45] op_sel_hi:[1,0]
	v_pk_mul_f32 v[40:41], v[12:13], v[40:41]
	v_pk_mul_f32 v[42:43], v[14:15], v[42:43]
	flat_store_dwordx4 v[34:35], v[40:43] nt
	v_mul_f32_e32 v39, 0x4f800000, v38
	v_cmp_gt_f32_e32 vcc, s53, v38
	v_pk_mul_f32 v[40:41], v[88:89], v[44:45] op_sel_hi:[1,0]
	v_pk_mul_f32 v[42:43], v[90:91], v[44:45] op_sel_hi:[1,0]
	v_pk_mul_f32 v[40:41], v[8:9], v[40:41]
	v_pk_mul_f32 v[42:43], v[10:11], v[42:43]
	flat_store_dwordx4 v[34:35], v[40:43] offset:16 nt
	s_nop 1
	v_pk_mul_f32 v[40:41], v[84:85], v[44:45] op_sel_hi:[1,0]
	v_pk_mul_f32 v[42:43], v[86:87], v[44:45] op_sel_hi:[1,0]
	v_pk_mul_f32 v[40:41], v[4:5], v[40:41]
	v_pk_mul_f32 v[42:43], v[6:7], v[42:43]
	flat_store_dwordx4 v[34:35], v[40:43] offset:512 nt
	s_nop 1
	v_pk_mul_f32 v[42:43], v[80:81], v[44:45] op_sel_hi:[1,0]
	v_cndmask_b32_e32 v45, v38, v39, vcc
	v_sqrt_f32_e32 v46, v45
	v_pk_mul_f32 v[38:39], v[82:83], v[44:45] op_sel_hi:[1,0]
	s_nop 0
	v_pk_mul_f32 v[40:41], v[2:3], v[38:39]
	v_pk_mul_f32 v[38:39], v[0:1], v[42:43]
	v_add_u32_e32 v42, -1, v46
	v_fma_f32 v43, -v42, v46, v45
	v_cmp_ge_f32_e64 s[4:5], 0, v43
	v_add_u32_e32 v43, 1, v46
	v_fma_f32 v44, -v43, v46, v45
	v_cndmask_b32_e64 v42, v46, v42, s[4:5]
	v_cmp_lt_f32_e64 s[4:5], 0, v44
	flat_store_dwordx4 v[34:35], v[38:41] offset:528 nt
	v_lshl_add_u64 v[34:35], v[34:35], 0, s[16:17]
	v_cndmask_b32_e64 v42, v42, v43, s[4:5]
	v_mul_f32_e32 v43, 0x37800000, v42
	v_cndmask_b32_e32 v42, v42, v43, vcc
	v_cmp_class_f32_e32 vcc, v45, v190
	s_nop 1
	v_cndmask_b32_e32 v42, v42, v45, vcc
	v_div_scale_f32 v43, s[4:5], v42, v42, 1.0
	v_rcp_f32_e32 v44, v43
	s_nop 0
	v_fma_f32 v38, -v43, v44, 1.0
	v_fmac_f32_e32 v44, v38, v44
	v_div_scale_f32 v38, vcc, 1.0, v42, 1.0
	v_mul_f32_e32 v39, v38, v44
	v_fma_f32 v40, -v43, v39, v38
	v_fmac_f32_e32 v39, v40, v44
	v_fma_f32 v38, -v43, v39, v38
	v_div_fmas_f32 v38, v38, v44, v39
	v_div_fixup_f32 v42, v38, v42, 1.0
	v_pk_mul_f32 v[38:39], v[76:77], v[42:43] op_sel_hi:[1,0]
	v_pk_mul_f32 v[40:41], v[78:79], v[42:43] op_sel_hi:[1,0]
	v_pk_mul_f32 v[38:39], v[12:13], v[38:39]
	v_pk_mul_f32 v[40:41], v[14:15], v[40:41]
	flat_store_dwordx4 v[34:35], v[38:41] nt
	v_cmp_gt_f32_e32 vcc, s53, v37
	s_nop 0
	v_pk_mul_f32 v[38:39], v[72:73], v[42:43] op_sel_hi:[1,0]
	v_pk_mul_f32 v[40:41], v[74:75], v[42:43] op_sel_hi:[1,0]
	v_pk_mul_f32 v[38:39], v[8:9], v[38:39]
	v_pk_mul_f32 v[40:41], v[10:11], v[40:41]
	flat_store_dwordx4 v[34:35], v[38:41] offset:16 nt
	s_nop 1
	v_pk_mul_f32 v[38:39], v[68:69], v[42:43] op_sel_hi:[1,0]
	v_pk_mul_f32 v[40:41], v[70:71], v[42:43] op_sel_hi:[1,0]
	v_pk_mul_f32 v[38:39], v[4:5], v[38:39]
	v_pk_mul_f32 v[40:41], v[6:7], v[40:41]
	flat_store_dwordx4 v[34:35], v[38:41] offset:512 nt
	s_nop 1
	v_mul_f32_e32 v40, 0x4f800000, v37
	v_cndmask_b32_e32 v37, v37, v40, vcc
	v_pk_mul_f32 v[38:39], v[64:65], v[42:43] op_sel_hi:[1,0]
	v_sqrt_f32_e32 v43, v37
	v_pk_mul_f32 v[38:39], v[0:1], v[38:39]
	v_pk_mul_f32 v[40:41], v[66:67], v[42:43] op_sel_hi:[1,0]
	v_add_u32_e32 v42, -1, v43
	v_fma_f32 v44, -v42, v43, v37
	v_cmp_ge_f32_e64 s[4:5], 0, v44
	v_add_u32_e32 v44, 1, v43
	v_pk_mul_f32 v[40:41], v[2:3], v[40:41]
	v_cndmask_b32_e64 v42, v43, v42, s[4:5]
	v_fma_f32 v43, -v44, v43, v37
	v_cmp_lt_f32_e64 s[4:5], 0, v43
	flat_store_dwordx4 v[34:35], v[38:41] offset:528 nt
	s_nop 0
	v_cndmask_b32_e64 v42, v42, v44, s[4:5]
	v_mul_f32_e32 v43, 0x37800000, v42
	v_cndmask_b32_e32 v42, v42, v43, vcc
	v_cmp_class_f32_e32 vcc, v37, v190
	s_nop 1
	v_cndmask_b32_e32 v37, v42, v37, vcc
	v_div_scale_f32 v44, s[4:5], v37, v37, 1.0
	v_rcp_f32_e32 v45, v44
	v_lshl_add_u64 v[42:43], v[34:35], 0, s[16:17]
	v_fma_f32 v34, -v44, v45, 1.0
	v_fmac_f32_e32 v45, v34, v45
	v_div_scale_f32 v34, vcc, 1.0, v37, 1.0
	v_mul_f32_e32 v35, v34, v45
	v_fma_f32 v38, -v44, v35, v34
	v_fmac_f32_e32 v35, v38, v45
	v_fma_f32 v34, -v44, v35, v34
	v_div_fmas_f32 v34, v34, v45, v35
	v_div_fixup_f32 v34, v34, v37, 1.0
	v_pk_mul_f32 v[38:39], v[60:61], v[34:35] op_sel_hi:[1,0]
	v_pk_mul_f32 v[40:41], v[62:63], v[34:35] op_sel_hi:[1,0]
	v_pk_mul_f32 v[38:39], v[12:13], v[38:39]
	v_pk_mul_f32 v[40:41], v[14:15], v[40:41]
	flat_store_dwordx4 v[42:43], v[38:41] nt
	s_nop 1
	v_pk_mul_f32 v[38:39], v[56:57], v[34:35] op_sel_hi:[1,0]
	v_pk_mul_f32 v[40:41], v[58:59], v[34:35] op_sel_hi:[1,0]
	v_pk_mul_f32 v[38:39], v[8:9], v[38:39]
	v_pk_mul_f32 v[40:41], v[10:11], v[40:41]
	flat_store_dwordx4 v[42:43], v[38:41] offset:16 nt
	s_nop 1
	v_pk_mul_f32 v[38:39], v[52:53], v[34:35] op_sel_hi:[1,0]
	v_pk_mul_f32 v[40:41], v[54:55], v[34:35] op_sel_hi:[1,0]
	v_pk_mul_f32 v[38:39], v[4:5], v[38:39]
	v_pk_mul_f32 v[40:41], v[6:7], v[40:41]
	flat_store_dwordx4 v[42:43], v[38:41] offset:512 nt
	s_nop 1
	v_pk_mul_f32 v[38:39], v[48:49], v[34:35] op_sel_hi:[1,0]
	s_waitcnt vmcnt(0)
	v_fmamk_f32 v35, v36, 0x3a000000, v189
	v_mul_f32_e32 v36, 0x4f800000, v35
	v_cmp_gt_f32_e32 vcc, s53, v35
	v_pk_mul_f32 v[24:25], v[24:25], v[34:35] op_sel_hi:[1,0]
	s_nop 0
	v_cndmask_b32_e32 v40, v35, v36, vcc
	v_sqrt_f32_e32 v41, v40
	v_pk_mul_f32 v[36:37], v[2:3], v[24:25]
	v_pk_mul_f32 v[34:35], v[0:1], v[38:39]
	flat_store_dwordx4 v[42:43], v[34:37] offset:528 nt
	v_add_u32_e32 v24, -1, v41
	v_fma_f32 v25, -v24, v41, v40
	v_cmp_ge_f32_e64 s[4:5], 0, v25
	v_add_u32_e32 v25, 1, v41
	v_fma_f32 v38, -v25, v41, v40
	v_cndmask_b32_e64 v24, v41, v24, s[4:5]
	v_cmp_lt_f32_e64 s[4:5], 0, v38
	s_nop 1
	v_cndmask_b32_e64 v24, v24, v25, s[4:5]
	v_mul_f32_e32 v25, 0x37800000, v24
	v_cndmask_b32_e32 v24, v24, v25, vcc
	v_cmp_class_f32_e32 vcc, v40, v190
	s_nop 1
	v_cndmask_b32_e32 v38, v24, v40, vcc
	v_div_scale_f32 v39, s[4:5], v38, v38, 1.0
	v_rcp_f32_e32 v40, v39
	v_lshl_add_u64 v[24:25], v[42:43], 0, s[16:17]
	s_mov_b64 s[4:5], -1
	v_fma_f32 v34, -v39, v40, 1.0
	v_fmac_f32_e32 v40, v34, v40
	v_div_scale_f32 v34, vcc, 1.0, v38, 1.0
	v_mul_f32_e32 v35, v34, v40
	v_fma_f32 v36, -v39, v35, v34
	v_fmac_f32_e32 v35, v36, v40
	v_fma_f32 v34, -v39, v35, v34
	v_div_fmas_f32 v34, v34, v40, v35
	v_div_fixup_f32 v34, v34, v38, 1.0
	v_pk_mul_f32 v[20:21], v[20:21], v[34:35] op_sel_hi:[1,0]
	v_pk_mul_f32 v[16:17], v[16:17], v[34:35] op_sel_hi:[1,0]
	v_pk_mul_f32 v[12:13], v[12:13], v[20:21]
	v_pk_mul_f32 v[14:15], v[14:15], v[16:17]
	flat_store_dwordx4 v[24:25], v[12:15] nt
	s_andn2_b64 vcc, exec, s[28:29]
	s_nop 0
	v_pk_mul_f32 v[12:13], v[26:27], v[34:35] op_sel_hi:[1,0]
	v_pk_mul_f32 v[14:15], v[18:19], v[34:35] op_sel_hi:[1,0]
	v_pk_mul_f32 v[8:9], v[8:9], v[12:13]
	v_pk_mul_f32 v[10:11], v[10:11], v[14:15]
	flat_store_dwordx4 v[24:25], v[8:11] offset:16 nt
	s_nop 1
	v_pk_mul_f32 v[8:9], v[30:31], v[34:35] op_sel_hi:[1,0]
	v_pk_mul_f32 v[10:11], v[22:23], v[34:35] op_sel_hi:[1,0]
	v_pk_mul_f32 v[4:5], v[4:5], v[8:9]
	v_pk_mul_f32 v[6:7], v[6:7], v[10:11]
	flat_store_dwordx4 v[24:25], v[4:7] offset:512 nt
	s_nop 1
	v_pk_mul_f32 v[4:5], v[32:33], v[34:35] op_sel_hi:[1,0]
	v_pk_mul_f32 v[6:7], v[28:29], v[34:35] op_sel_hi:[1,0]
	v_pk_mul_f32 v[0:1], v[0:1], v[4:5]
	v_pk_mul_f32 v[2:3], v[2:3], v[6:7]
	flat_store_dwordx4 v[24:25], v[0:3] offset:528 nt
	s_nop 1
	v_lshl_add_u64 v[0:1], v[24:25], 0, s[20:21]
	s_cbranch_vccnz .LBB0_668
	s_andn2_b64 vcc, exec, s[12:13]
	s_cbranch_vccnz .LBB0_667
	s_barrier
	s_branch .LBB0_667
